# P5 branch-merge epilogue rewritten by hand (packed f32 math, branch-tile loads several rows ahead)
# speedup vs baseline: 1.0021x; 1.0021x over previous
;     __device__ __forceinline__ void operator()(const pg8::f32x4 (&acc)[2][2][4][2], const pg8::Unit& u, int wr, int wc, int fr, int fq) const {
;         const int row0 = u.pm * 256 + wr * 64 + fr, col0 = u.pn * 128 + wc * 32 + 8 * fq;
;         const pg8::f32x4 wa0 = *(const pg8::f32x4*)(wa + col0), wa1 = *(const pg8::f32x4*)(wa + col0 + 4), ws0 = *(const pg8::f32x4*)(wsn + col0), ws1 = *(const pg8::f32x4*)(wsn + col0 + 4);
;         float rsv[8], rav[8], rbv[8];
; #pragma unroll
;         for (int q = 0; q < 8; ++q) { const int row = row0 + (q >> 2) * 128 + (q & 3) * 16; rsv[q] = rstd[row]; rav[q] = rowsa[row]; rbv[q] = rowsb[row]; }
; #pragma unroll
;         for (int p = 0; p < 4; ++p) {
;             u32x4 awv[2], swv[2];
; #pragma unroll
;             for (int m2 = 0; m2 < 2; ++m2) { const int q = p * 2 + m2; const size_t off = (size_t)(row0 + (q >> 2) * 128 + (q & 3) * 16) * DM + col0; awv[m2] = *(const u32x4*)(ATT + off); swv[m2] = *(const u32x4*)(SSM + off); }
;             asm volatile("" : "+v"(awv[0]), "+v"(awv[1]), "+v"(swv[0]), "+v"(swv[1]));
; #pragma unroll
;             for (int m2 = 0; m2 < 2; ++m2) { const int q = p * 2 + m2, ai = q >> 2, m = q & 3; const int row = row0 + ai * 128 + m * 16; const size_t off = (size_t)row * DM + col0;
;                 const u32x4 aw = awv[m2], sw = swv[m2];
;                 const float rs = rsv[q], ra = __builtin_amdgcn_rsqf(rav[q] * (1.0f / DM) + EPS), rb = __builtin_amdgcn_rsqf(rbv[q] * (1.0f / DM) + EPS);
;                 const float av[8] = {bf_lo(aw.x), bf_hi(aw.x), bf_lo(aw.y), bf_hi(aw.y), bf_lo(aw.z), bf_hi(aw.z), bf_lo(aw.w), bf_hi(aw.w)};
;                 const float sv[8] = {bf_lo(sw.x), bf_hi(sw.x), bf_lo(sw.y), bf_hi(sw.y), bf_lo(sw.z), bf_hi(sw.z), bf_lo(sw.w), bf_hi(sw.w)};
;                 float o[8];
; #pragma unroll
;                 for (int n = 0; n < 2; ++n)
; #pragma unroll
;                     for (int e = 0; e < 4; ++e) { const float wl = n ? wa1[e] : wa0[e], vl = n ? ws1[e] : ws0[e];
;                         o[n * 4 + e] = fast_sigmoid(acc[ai][0][m][n][e] * rs) * av[n * 4 + e] * (ra * wl) + fast_sigmoid(acc[ai][1][m][n][e] * rs) * sv[n * 4 + e] * (rb * vl); }
;                 u32x4 w; w.x = cvt_pk(o[0], o[1]); w.y = cvt_pk(o[2], o[3]); w.z = cvt_pk(o[4], o[5]); w.w = cvt_pk(o[6], o[7]);
;                 *(u32x4*)(MG + off) = w; }
.LBB0_507:
	v_lshl_add_u32 v178, s28, 8, v205
	v_lshl_or_b32 v179, s29, 7, v207
	v_mov_b32_e32 v183, 0
	v_lshlrev_b32_e32 v182, 2, v179
	v_lshl_add_u64 v[180:181], s[44:45], 0, v[182:183]
	v_lshl_add_u64 v[184:185], s[46:47], 0, v[182:183]
	global_load_dwordx4 v[136:139], v[180:181], off
	global_load_dwordx4 v[140:143], v[180:181], off offset:16
	global_load_dwordx4 v[144:147], v[184:185], off
	global_load_dwordx4 v[148:151], v[184:185], off offset:16
	v_lshlrev_b32_e32 v182, 2, v178
	v_lshl_add_u64 v[180:181], s[58:59], 0, v[182:183]
	v_lshl_add_u64 v[184:185], s[60:61], 0, v[182:183]
	v_lshl_add_u64 v[186:187], s[10:11], 0, v[182:183]
	global_load_dword v212, v[180:181], off
	global_load_dword v213, v[184:185], off
	global_load_dword v214, v[186:187], off
	global_load_dword v215, v[180:181], off offset:64
	global_load_dword v216, v[184:185], off offset:64
	global_load_dword v217, v[186:187], off offset:64
	global_load_dword v218, v[180:181], off offset:128
	global_load_dword v219, v[184:185], off offset:128
	global_load_dword v220, v[186:187], off offset:128
	global_load_dword v221, v[180:181], off offset:192
	global_load_dword v222, v[184:185], off offset:192
	global_load_dword v223, v[186:187], off offset:192
	v_lshlrev_b32_e32 v188, 11, v178
	v_lshl_add_u32 v188, v179, 1, v188
	v_mov_b32_e32 v189, 0
	v_lshl_add_u64 v[190:191], s[8:9], 0, v[188:189]
	v_lshl_add_u64 v[192:193], s[52:53], 0, v[188:189]
	v_lshl_add_u64 v[188:189], s[48:49], 0, v[188:189]
	s_mov_b32 s70, 0x3f800000
	s_mov_b32 s71, 0x3f800000
	s_mov_b32 s72, 0x8000
	s_mov_b32 s73, 0
	s_mov_b32 s74, 0x28000
	s_mov_b32 s75, 0
	v_mov_b32_e32 v194, 0x3a800000
	global_load_dwordx4 v[152:155], v[190:191], off
	global_load_dwordx4 v[156:159], v[192:193], off
	v_lshl_add_u64 v[190:191], v[190:191], 0, s[72:73]
	v_lshl_add_u64 v[192:193], v[192:193], 0, s[72:73]
	global_load_dwordx4 v[196:199], v[190:191], off
	global_load_dwordx4 v[252:255], v[192:193], off
	v_lshl_add_u64 v[190:191], v[190:191], 0, s[72:73]
	v_lshl_add_u64 v[192:193], v[192:193], 0, s[72:73]
	global_load_dwordx4 v[240:243], v[190:191], off
	global_load_dwordx4 v[244:247], v[192:193], off
	s_waitcnt vmcnt(15)
	v_fmaak_f32 v213, v194, v213, 0x358637bd
	v_fmaak_f32 v214, v194, v214, 0x358637bd
	v_mul_f32_e32 v212, 0xbfb8aa3b, v212
	v_rsq_f32_e32 v213, v213
	v_rsq_f32_e32 v214, v214
	v_pk_mul_f32 v[132:133], v[132:133], v[212:213] op_sel_hi:[1,0]
	v_pk_mul_f32 v[134:135], v[134:135], v[212:213] op_sel_hi:[1,0]
	v_pk_mul_f32 v[124:125], v[124:125], v[212:213] op_sel_hi:[1,0]
	v_pk_mul_f32 v[126:127], v[126:127], v[212:213] op_sel_hi:[1,0]
	v_pk_mul_f32 v[128:129], v[128:129], v[212:213] op_sel_hi:[1,0]
	v_pk_mul_f32 v[130:131], v[130:131], v[212:213] op_sel_hi:[1,0]
	v_pk_mul_f32 v[120:121], v[120:121], v[212:213] op_sel_hi:[1,0]
	v_pk_mul_f32 v[122:123], v[122:123], v[212:213] op_sel_hi:[1,0]
	v_exp_f32_e32 v132, v132
	v_exp_f32_e32 v133, v133
	v_exp_f32_e32 v134, v134
	v_exp_f32_e32 v135, v135
	v_exp_f32_e32 v124, v124
	v_exp_f32_e32 v125, v125
	v_exp_f32_e32 v126, v126
	v_exp_f32_e32 v127, v127
	v_exp_f32_e32 v128, v128
	v_exp_f32_e32 v129, v129
	v_exp_f32_e32 v130, v130
	v_exp_f32_e32 v131, v131
	v_exp_f32_e32 v120, v120
	v_exp_f32_e32 v121, v121
	v_exp_f32_e32 v122, v122
	v_exp_f32_e32 v123, v123
	v_pk_add_f32 v[132:133], v[132:133], s[70:71]
	v_pk_add_f32 v[134:135], v[134:135], s[70:71]
	v_pk_add_f32 v[124:125], v[124:125], s[70:71]
	v_pk_add_f32 v[126:127], v[126:127], s[70:71]
	v_pk_add_f32 v[128:129], v[128:129], s[70:71]
	v_pk_add_f32 v[130:131], v[130:131], s[70:71]
	v_pk_add_f32 v[120:121], v[120:121], s[70:71]
	v_pk_add_f32 v[122:123], v[122:123], s[70:71]
	v_rcp_f32_e32 v132, v132
	v_rcp_f32_e32 v133, v133
	v_rcp_f32_e32 v134, v134
	v_rcp_f32_e32 v135, v135
	v_rcp_f32_e32 v124, v124
	v_rcp_f32_e32 v125, v125
	v_rcp_f32_e32 v126, v126
	v_rcp_f32_e32 v127, v127
	v_rcp_f32_e32 v128, v128
	v_rcp_f32_e32 v129, v129
	v_rcp_f32_e32 v130, v130
	v_rcp_f32_e32 v131, v131
	v_rcp_f32_e32 v120, v120
	v_rcp_f32_e32 v121, v121
	v_rcp_f32_e32 v122, v122
	v_rcp_f32_e32 v123, v123
	s_waitcnt vmcnt(4)
	v_lshlrev_b32_e32 v36, 16, v152
	v_and_b32_e32 v37, 0xffff0000, v152
	v_lshlrev_b32_e32 v38, 16, v156
	v_and_b32_e32 v39, 0xffff0000, v156
	v_lshlrev_b32_e32 v48, 16, v153
	v_and_b32_e32 v49, 0xffff0000, v153
	v_lshlrev_b32_e32 v50, 16, v157
	v_and_b32_e32 v51, 0xffff0000, v157
	v_pk_mul_f32 v[36:37], v[36:37], v[136:137]
	v_pk_mul_f32 v[38:39], v[38:39], v[144:145]
	v_pk_mul_f32 v[48:49], v[48:49], v[138:139]
	v_pk_mul_f32 v[50:51], v[50:51], v[146:147]
	v_pk_mul_f32 v[132:133], v[132:133], v[36:37]
	v_pk_mul_f32 v[128:129], v[128:129], v[38:39]
	v_pk_mul_f32 v[134:135], v[134:135], v[48:49]
	v_pk_mul_f32 v[130:131], v[130:131], v[50:51]
	v_pk_mul_f32 v[132:133], v[132:133], v[212:213] op_sel:[0,1]
	v_pk_mul_f32 v[134:135], v[134:135], v[212:213] op_sel:[0,1]
	v_pk_fma_f32 v[132:133], v[128:129], v[214:215], v[132:133] op_sel_hi:[1,0,1]
	v_pk_fma_f32 v[134:135], v[130:131], v[214:215], v[134:135] op_sel_hi:[1,0,1]
	v_lshlrev_b32_e32 v36, 16, v154
	v_and_b32_e32 v37, 0xffff0000, v154
	v_lshlrev_b32_e32 v38, 16, v158
	v_and_b32_e32 v39, 0xffff0000, v158
	v_lshlrev_b32_e32 v48, 16, v155
	v_and_b32_e32 v49, 0xffff0000, v155
	v_lshlrev_b32_e32 v50, 16, v159
	v_and_b32_e32 v51, 0xffff0000, v159
	v_pk_mul_f32 v[36:37], v[36:37], v[140:141]
	v_pk_mul_f32 v[38:39], v[38:39], v[148:149]
	v_pk_mul_f32 v[48:49], v[48:49], v[142:143]
	v_pk_mul_f32 v[50:51], v[50:51], v[150:151]
	v_pk_mul_f32 v[124:125], v[124:125], v[36:37]
	v_pk_mul_f32 v[120:121], v[120:121], v[38:39]
	v_pk_mul_f32 v[126:127], v[126:127], v[48:49]
	v_pk_mul_f32 v[122:123], v[122:123], v[50:51]
	v_pk_mul_f32 v[124:125], v[124:125], v[212:213] op_sel:[0,1]
	v_pk_mul_f32 v[126:127], v[126:127], v[212:213] op_sel:[0,1]
	v_pk_fma_f32 v[124:125], v[120:121], v[214:215], v[124:125] op_sel_hi:[1,0,1]
	v_pk_fma_f32 v[126:127], v[122:123], v[214:215], v[126:127] op_sel_hi:[1,0,1]
	s_nop 0
	v_cvt_pk_bf16_f32 v132, v132, v133
	v_cvt_pk_bf16_f32 v133, v134, v135
	v_cvt_pk_bf16_f32 v134, v124, v125
	v_cvt_pk_bf16_f32 v135, v126, v127
	global_store_dwordx4 v[188:189], v[132:135], off
	global_load_dword v212, v[180:181], off offset:512
	global_load_dword v213, v[184:185], off offset:512
	global_load_dword v214, v[186:187], off offset:512
	v_lshl_add_u64 v[190:191], v[190:191], 0, s[72:73]
	v_lshl_add_u64 v[192:193], v[192:193], 0, s[72:73]
	global_load_dwordx4 v[248:251], v[190:191], off
	global_load_dwordx4 v[152:155], v[192:193], off
	v_lshl_add_u64 v[190:191], v[190:191], 0, s[74:75]
	v_lshl_add_u64 v[192:193], v[192:193], 0, s[74:75]
	global_load_dwordx4 v[156:159], v[190:191], off
	global_load_dwordx4 v[124:127], v[192:193], off
	v_lshl_add_u64 v[190:191], v[190:191], 0, s[72:73]
	v_lshl_add_u64 v[192:193], v[192:193], 0, s[72:73]
	global_load_dwordx4 v[128:131], v[190:191], off
	global_load_dwordx4 v[120:123], v[192:193], off
	s_waitcnt vmcnt(22)
;     __device__ __forceinline__ void operator()(const pg8::f32x4 (&acc)[2][2][4][2], const pg8::Unit& u, int wr, int wc, int fr, int fq) const {
;         const int row0 = u.pm * 256 + wr * 64 + fr, col0 = u.pn * 128 + wc * 32 + 8 * fq;
;         const pg8::f32x4 wa0 = *(const pg8::f32x4*)(wa + col0), wa1 = *(const pg8::f32x4*)(wa + col0 + 4), ws0 = *(const pg8::f32x4*)(wsn + col0), ws1 = *(const pg8::f32x4*)(wsn + col0 + 4);
;         float rsv[8], rav[8], rbv[8];
; #pragma unroll
;         for (int q = 0; q < 8; ++q) { const int row = row0 + (q >> 2) * 128 + (q & 3) * 16; rsv[q] = rstd[row]; rav[q] = rowsa[row]; rbv[q] = rowsb[row]; }
; #pragma unroll
;         for (int p = 0; p < 4; ++p) {
;             u32x4 awv[2], swv[2];
; #pragma unroll
;             for (int m2 = 0; m2 < 2; ++m2) { const int q = p * 2 + m2; const size_t off = (size_t)(row0 + (q >> 2) * 128 + (q & 3) * 16) * DM + col0; awv[m2] = *(const u32x4*)(ATT + off); swv[m2] = *(const u32x4*)(SSM + off); }
;             asm volatile("" : "+v"(awv[0]), "+v"(awv[1]), "+v"(swv[0]), "+v"(swv[1]));
; #pragma unroll
;             for (int m2 = 0; m2 < 2; ++m2) { const int q = p * 2 + m2, ai = q >> 2, m = q & 3; const int row = row0 + ai * 128 + m * 16; const size_t off = (size_t)row * DM + col0;
;                 const u32x4 aw = awv[m2], sw = swv[m2];
;                 const float rs = rsv[q], ra = __builtin_amdgcn_rsqf(rav[q] * (1.0f / DM) + EPS), rb = __builtin_amdgcn_rsqf(rbv[q] * (1.0f / DM) + EPS);
;                 const float av[8] = {bf_lo(aw.x), bf_hi(aw.x), bf_lo(aw.y), bf_hi(aw.y), bf_lo(aw.z), bf_hi(aw.z), bf_lo(aw.w), bf_hi(aw.w)};
;                 const float sv[8] = {bf_lo(sw.x), bf_hi(sw.x), bf_lo(sw.y), bf_hi(sw.y), bf_lo(sw.z), bf_hi(sw.z), bf_lo(sw.w), bf_hi(sw.w)};
;                 float o[8];
; #pragma unroll
;                 for (int n = 0; n < 2; ++n)
; #pragma unroll
;                     for (int e = 0; e < 4; ++e) { const float wl = n ? wa1[e] : wa0[e], vl = n ? ws1[e] : ws0[e];
;                         o[n * 4 + e] = fast_sigmoid(acc[ai][0][m][n][e] * rs) * av[n * 4 + e] * (ra * wl) + fast_sigmoid(acc[ai][1][m][n][e] * rs) * sv[n * 4 + e] * (rb * vl); }
;                 u32x4 w; w.x = cvt_pk(o[0], o[1]); w.y = cvt_pk(o[2], o[3]); w.z = cvt_pk(o[4], o[5]); w.w = cvt_pk(o[6], o[7]);
;                 *(u32x4*)(MG + off) = w; }
	v_fmaak_f32 v216, v194, v216, 0x358637bd
	v_fmaak_f32 v217, v194, v217, 0x358637bd
	v_mul_f32_e32 v215, 0xbfb8aa3b, v215
	v_rsq_f32_e32 v216, v216
	v_rsq_f32_e32 v217, v217
	v_pk_mul_f32 v[116:117], v[116:117], v[214:215] op_sel:[0,1]
	v_pk_mul_f32 v[118:119], v[118:119], v[214:215] op_sel:[0,1]
	v_pk_mul_f32 v[108:109], v[108:109], v[214:215] op_sel:[0,1]
	v_pk_mul_f32 v[110:111], v[110:111], v[214:215] op_sel:[0,1]
	v_pk_mul_f32 v[112:113], v[112:113], v[214:215] op_sel:[0,1]
	v_pk_mul_f32 v[114:115], v[114:115], v[214:215] op_sel:[0,1]
	v_pk_mul_f32 v[104:105], v[104:105], v[214:215] op_sel:[0,1]
	v_pk_mul_f32 v[106:107], v[106:107], v[214:215] op_sel:[0,1]
	v_exp_f32_e32 v116, v116
	v_exp_f32_e32 v117, v117
	v_exp_f32_e32 v118, v118
	v_exp_f32_e32 v119, v119
	v_exp_f32_e32 v108, v108
	v_exp_f32_e32 v109, v109
	v_exp_f32_e32 v110, v110
	v_exp_f32_e32 v111, v111
	v_exp_f32_e32 v112, v112
	v_exp_f32_e32 v113, v113
	v_exp_f32_e32 v114, v114
	v_exp_f32_e32 v115, v115
	v_exp_f32_e32 v104, v104
	v_exp_f32_e32 v105, v105
	v_exp_f32_e32 v106, v106
	v_exp_f32_e32 v107, v107
	v_pk_add_f32 v[116:117], v[116:117], s[70:71]
	v_pk_add_f32 v[118:119], v[118:119], s[70:71]
	v_pk_add_f32 v[108:109], v[108:109], s[70:71]
	v_pk_add_f32 v[110:111], v[110:111], s[70:71]
	v_pk_add_f32 v[112:113], v[112:113], s[70:71]
	v_pk_add_f32 v[114:115], v[114:115], s[70:71]
	v_pk_add_f32 v[104:105], v[104:105], s[70:71]
	v_pk_add_f32 v[106:107], v[106:107], s[70:71]
	v_rcp_f32_e32 v116, v116
	v_rcp_f32_e32 v117, v117
	v_rcp_f32_e32 v118, v118
	v_rcp_f32_e32 v119, v119
	v_rcp_f32_e32 v108, v108
	v_rcp_f32_e32 v109, v109
	v_rcp_f32_e32 v110, v110
	v_rcp_f32_e32 v111, v111
	v_rcp_f32_e32 v112, v112
	v_rcp_f32_e32 v113, v113
	v_rcp_f32_e32 v114, v114
	v_rcp_f32_e32 v115, v115
	v_rcp_f32_e32 v104, v104
	v_rcp_f32_e32 v105, v105
	v_rcp_f32_e32 v106, v106
	v_rcp_f32_e32 v107, v107
	s_waitcnt vmcnt(12)
	v_lshlrev_b32_e32 v36, 16, v196
	v_and_b32_e32 v37, 0xffff0000, v196
	v_lshlrev_b32_e32 v38, 16, v252
	v_and_b32_e32 v39, 0xffff0000, v252
	v_lshlrev_b32_e32 v48, 16, v197
	v_and_b32_e32 v49, 0xffff0000, v197
	v_lshlrev_b32_e32 v50, 16, v253
	v_and_b32_e32 v51, 0xffff0000, v253
	v_pk_mul_f32 v[36:37], v[36:37], v[136:137]
	v_pk_mul_f32 v[38:39], v[38:39], v[144:145]
	v_pk_mul_f32 v[48:49], v[48:49], v[138:139]
	v_pk_mul_f32 v[50:51], v[50:51], v[146:147]
	v_pk_mul_f32 v[116:117], v[116:117], v[36:37]
	v_pk_mul_f32 v[112:113], v[112:113], v[38:39]
	v_pk_mul_f32 v[118:119], v[118:119], v[48:49]
	v_pk_mul_f32 v[114:115], v[114:115], v[50:51]
	v_pk_mul_f32 v[116:117], v[116:117], v[216:217] op_sel_hi:[1,0]
	v_pk_mul_f32 v[118:119], v[118:119], v[216:217] op_sel_hi:[1,0]
	v_pk_fma_f32 v[116:117], v[112:113], v[216:217], v[116:117] op_sel:[0,1,0]
	v_pk_fma_f32 v[118:119], v[114:115], v[216:217], v[118:119] op_sel:[0,1,0]
	v_lshlrev_b32_e32 v36, 16, v198
	v_and_b32_e32 v37, 0xffff0000, v198
	v_lshlrev_b32_e32 v38, 16, v254
	v_and_b32_e32 v39, 0xffff0000, v254
	v_lshlrev_b32_e32 v48, 16, v199
	v_and_b32_e32 v49, 0xffff0000, v199
	v_lshlrev_b32_e32 v50, 16, v255
	v_and_b32_e32 v51, 0xffff0000, v255
	v_pk_mul_f32 v[36:37], v[36:37], v[140:141]
	v_pk_mul_f32 v[38:39], v[38:39], v[148:149]
	v_pk_mul_f32 v[48:49], v[48:49], v[142:143]
	v_pk_mul_f32 v[50:51], v[50:51], v[150:151]
	v_pk_mul_f32 v[108:109], v[108:109], v[36:37]
	v_pk_mul_f32 v[104:105], v[104:105], v[38:39]
	v_pk_mul_f32 v[110:111], v[110:111], v[48:49]
	v_pk_mul_f32 v[106:107], v[106:107], v[50:51]
	v_pk_mul_f32 v[108:109], v[108:109], v[216:217] op_sel_hi:[1,0]
	v_pk_mul_f32 v[110:111], v[110:111], v[216:217] op_sel_hi:[1,0]
	v_pk_fma_f32 v[108:109], v[104:105], v[216:217], v[108:109] op_sel:[0,1,0]
	v_pk_fma_f32 v[110:111], v[106:107], v[216:217], v[110:111] op_sel:[0,1,0]
	s_nop 0
	v_cvt_pk_bf16_f32 v116, v116, v117
	v_cvt_pk_bf16_f32 v117, v118, v119
	v_cvt_pk_bf16_f32 v118, v108, v109
	v_cvt_pk_bf16_f32 v119, v110, v111
	v_lshl_add_u64 v[188:189], v[188:189], 0, s[72:73]
	global_store_dwordx4 v[188:189], v[116:119], off
	global_load_dword v215, v[180:181], off offset:576
	global_load_dword v216, v[184:185], off offset:576
	global_load_dword v217, v[186:187], off offset:576
	v_lshl_add_u64 v[190:191], v[190:191], 0, s[72:73]
	v_lshl_add_u64 v[192:193], v[192:193], 0, s[72:73]
	global_load_dwordx4 v[196:199], v[190:191], off
	global_load_dwordx4 v[252:255], v[192:193], off
	v_lshl_add_u64 v[190:191], v[190:191], 0, s[72:73]
	v_lshl_add_u64 v[192:193], v[192:193], 0, s[72:73]
	global_load_dwordx4 v[108:111], v[190:191], off
	global_load_dwordx4 v[112:115], v[192:193], off
	s_waitcnt vmcnt(27)
	v_fmaak_f32 v219, v194, v219, 0x358637bd
	v_fmaak_f32 v220, v194, v220, 0x358637bd
	v_mul_f32_e32 v218, 0xbfb8aa3b, v218
	v_rsq_f32_e32 v219, v219
	v_rsq_f32_e32 v220, v220
	v_pk_mul_f32 v[100:101], v[100:101], v[218:219] op_sel_hi:[1,0]
	v_pk_mul_f32 v[102:103], v[102:103], v[218:219] op_sel_hi:[1,0]
	v_pk_mul_f32 v[92:93], v[92:93], v[218:219] op_sel_hi:[1,0]
	v_pk_mul_f32 v[94:95], v[94:95], v[218:219] op_sel_hi:[1,0]
	v_pk_mul_f32 v[96:97], v[96:97], v[218:219] op_sel_hi:[1,0]
	v_pk_mul_f32 v[98:99], v[98:99], v[218:219] op_sel_hi:[1,0]
	v_pk_mul_f32 v[88:89], v[88:89], v[218:219] op_sel_hi:[1,0]
	v_pk_mul_f32 v[90:91], v[90:91], v[218:219] op_sel_hi:[1,0]
	v_exp_f32_e32 v100, v100
	v_exp_f32_e32 v101, v101
	v_exp_f32_e32 v102, v102
	v_exp_f32_e32 v103, v103
	v_exp_f32_e32 v92, v92
	v_exp_f32_e32 v93, v93
	v_exp_f32_e32 v94, v94
	v_exp_f32_e32 v95, v95
	v_exp_f32_e32 v96, v96
	v_exp_f32_e32 v97, v97
	v_exp_f32_e32 v98, v98
	v_exp_f32_e32 v99, v99
	v_exp_f32_e32 v88, v88
	v_exp_f32_e32 v89, v89
	v_exp_f32_e32 v90, v90
	v_exp_f32_e32 v91, v91
	v_pk_add_f32 v[100:101], v[100:101], s[70:71]
	v_pk_add_f32 v[102:103], v[102:103], s[70:71]
	v_pk_add_f32 v[92:93], v[92:93], s[70:71]
	v_pk_add_f32 v[94:95], v[94:95], s[70:71]
	v_pk_add_f32 v[96:97], v[96:97], s[70:71]
	v_pk_add_f32 v[98:99], v[98:99], s[70:71]
	v_pk_add_f32 v[88:89], v[88:89], s[70:71]
	v_pk_add_f32 v[90:91], v[90:91], s[70:71]
	v_rcp_f32_e32 v100, v100
	v_rcp_f32_e32 v101, v101
	v_rcp_f32_e32 v102, v102
	v_rcp_f32_e32 v103, v103
	v_rcp_f32_e32 v92, v92
	v_rcp_f32_e32 v93, v93
	v_rcp_f32_e32 v94, v94
	v_rcp_f32_e32 v95, v95
	v_rcp_f32_e32 v96, v96
	v_rcp_f32_e32 v97, v97
	v_rcp_f32_e32 v98, v98
	v_rcp_f32_e32 v99, v99
	v_rcp_f32_e32 v88, v88
	v_rcp_f32_e32 v89, v89
	v_rcp_f32_e32 v90, v90
	v_rcp_f32_e32 v91, v91
	s_waitcnt vmcnt(18)
;     __device__ __forceinline__ void operator()(const pg8::f32x4 (&acc)[2][2][4][2], const pg8::Unit& u, int wr, int wc, int fr, int fq) const {
;         const int row0 = u.pm * 256 + wr * 64 + fr, col0 = u.pn * 128 + wc * 32 + 8 * fq;
;         const pg8::f32x4 wa0 = *(const pg8::f32x4*)(wa + col0), wa1 = *(const pg8::f32x4*)(wa + col0 + 4), ws0 = *(const pg8::f32x4*)(wsn + col0), ws1 = *(const pg8::f32x4*)(wsn + col0 + 4);
;         float rsv[8], rav[8], rbv[8];
; #pragma unroll
;         for (int q = 0; q < 8; ++q) { const int row = row0 + (q >> 2) * 128 + (q & 3) * 16; rsv[q] = rstd[row]; rav[q] = rowsa[row]; rbv[q] = rowsb[row]; }
; #pragma unroll
;         for (int p = 0; p < 4; ++p) {
;             u32x4 awv[2], swv[2];
; #pragma unroll
;             for (int m2 = 0; m2 < 2; ++m2) { const int q = p * 2 + m2; const size_t off = (size_t)(row0 + (q >> 2) * 128 + (q & 3) * 16) * DM + col0; awv[m2] = *(const u32x4*)(ATT + off); swv[m2] = *(const u32x4*)(SSM + off); }
;             asm volatile("" : "+v"(awv[0]), "+v"(awv[1]), "+v"(swv[0]), "+v"(swv[1]));
; #pragma unroll
;             for (int m2 = 0; m2 < 2; ++m2) { const int q = p * 2 + m2, ai = q >> 2, m = q & 3; const int row = row0 + ai * 128 + m * 16; const size_t off = (size_t)row * DM + col0;
;                 const u32x4 aw = awv[m2], sw = swv[m2];
;                 const float rs = rsv[q], ra = __builtin_amdgcn_rsqf(rav[q] * (1.0f / DM) + EPS), rb = __builtin_amdgcn_rsqf(rbv[q] * (1.0f / DM) + EPS);
;                 const float av[8] = {bf_lo(aw.x), bf_hi(aw.x), bf_lo(aw.y), bf_hi(aw.y), bf_lo(aw.z), bf_hi(aw.z), bf_lo(aw.w), bf_hi(aw.w)};
;                 const float sv[8] = {bf_lo(sw.x), bf_hi(sw.x), bf_lo(sw.y), bf_hi(sw.y), bf_lo(sw.z), bf_hi(sw.z), bf_lo(sw.w), bf_hi(sw.w)};
;                 float o[8];
; #pragma unroll
;                 for (int n = 0; n < 2; ++n)
; #pragma unroll
;                     for (int e = 0; e < 4; ++e) { const float wl = n ? wa1[e] : wa0[e], vl = n ? ws1[e] : ws0[e];
;                         o[n * 4 + e] = fast_sigmoid(acc[ai][0][m][n][e] * rs) * av[n * 4 + e] * (ra * wl) + fast_sigmoid(acc[ai][1][m][n][e] * rs) * sv[n * 4 + e] * (rb * vl); }
;                 u32x4 w; w.x = cvt_pk(o[0], o[1]); w.y = cvt_pk(o[2], o[3]); w.z = cvt_pk(o[4], o[5]); w.w = cvt_pk(o[6], o[7]);
;                 *(u32x4*)(MG + off) = w; }
	v_lshlrev_b32_e32 v36, 16, v240
	v_and_b32_e32 v37, 0xffff0000, v240
	v_lshlrev_b32_e32 v38, 16, v244
	v_and_b32_e32 v39, 0xffff0000, v244
	v_lshlrev_b32_e32 v48, 16, v241
	v_and_b32_e32 v49, 0xffff0000, v241
	v_lshlrev_b32_e32 v50, 16, v245
	v_and_b32_e32 v51, 0xffff0000, v245
	v_pk_mul_f32 v[36:37], v[36:37], v[136:137]
	v_pk_mul_f32 v[38:39], v[38:39], v[144:145]
	v_pk_mul_f32 v[48:49], v[48:49], v[138:139]
	v_pk_mul_f32 v[50:51], v[50:51], v[146:147]
	v_pk_mul_f32 v[100:101], v[100:101], v[36:37]
	v_pk_mul_f32 v[96:97], v[96:97], v[38:39]
	v_pk_mul_f32 v[102:103], v[102:103], v[48:49]
	v_pk_mul_f32 v[98:99], v[98:99], v[50:51]
	v_pk_mul_f32 v[100:101], v[100:101], v[218:219] op_sel:[0,1]
	v_pk_mul_f32 v[102:103], v[102:103], v[218:219] op_sel:[0,1]
	v_pk_fma_f32 v[100:101], v[96:97], v[220:221], v[100:101] op_sel_hi:[1,0,1]
	v_pk_fma_f32 v[102:103], v[98:99], v[220:221], v[102:103] op_sel_hi:[1,0,1]
	v_lshlrev_b32_e32 v36, 16, v242
	v_and_b32_e32 v37, 0xffff0000, v242
	v_lshlrev_b32_e32 v38, 16, v246
	v_and_b32_e32 v39, 0xffff0000, v246
	v_lshlrev_b32_e32 v48, 16, v243
	v_and_b32_e32 v49, 0xffff0000, v243
	v_lshlrev_b32_e32 v50, 16, v247
	v_and_b32_e32 v51, 0xffff0000, v247
	v_pk_mul_f32 v[36:37], v[36:37], v[140:141]
	v_pk_mul_f32 v[38:39], v[38:39], v[148:149]
	v_pk_mul_f32 v[48:49], v[48:49], v[142:143]
	v_pk_mul_f32 v[50:51], v[50:51], v[150:151]
	v_pk_mul_f32 v[92:93], v[92:93], v[36:37]
	v_pk_mul_f32 v[88:89], v[88:89], v[38:39]
	v_pk_mul_f32 v[94:95], v[94:95], v[48:49]
	v_pk_mul_f32 v[90:91], v[90:91], v[50:51]
	v_pk_mul_f32 v[92:93], v[92:93], v[218:219] op_sel:[0,1]
	v_pk_mul_f32 v[94:95], v[94:95], v[218:219] op_sel:[0,1]
	v_pk_fma_f32 v[92:93], v[88:89], v[220:221], v[92:93] op_sel_hi:[1,0,1]
	v_pk_fma_f32 v[94:95], v[90:91], v[220:221], v[94:95] op_sel_hi:[1,0,1]
	s_nop 0
	v_cvt_pk_bf16_f32 v100, v100, v101
	v_cvt_pk_bf16_f32 v101, v102, v103
	v_cvt_pk_bf16_f32 v102, v92, v93
	v_cvt_pk_bf16_f32 v103, v94, v95
	v_lshl_add_u64 v[188:189], v[188:189], 0, s[72:73]
	global_store_dwordx4 v[188:189], v[100:103], off
	global_load_dword v218, v[180:181], off offset:640
	global_load_dword v219, v[184:185], off offset:640
	global_load_dword v220, v[186:187], off offset:640
	s_waitcnt vmcnt(28)
	v_fmaak_f32 v222, v194, v222, 0x358637bd
	v_fmaak_f32 v223, v194, v223, 0x358637bd
	v_mul_f32_e32 v221, 0xbfb8aa3b, v221
	v_rsq_f32_e32 v222, v222
	v_rsq_f32_e32 v223, v223
	v_pk_mul_f32 v[84:85], v[84:85], v[220:221] op_sel:[0,1]
	v_pk_mul_f32 v[86:87], v[86:87], v[220:221] op_sel:[0,1]
	v_pk_mul_f32 v[76:77], v[76:77], v[220:221] op_sel:[0,1]
	v_pk_mul_f32 v[78:79], v[78:79], v[220:221] op_sel:[0,1]
	v_pk_mul_f32 v[80:81], v[80:81], v[220:221] op_sel:[0,1]
	v_pk_mul_f32 v[82:83], v[82:83], v[220:221] op_sel:[0,1]
	v_pk_mul_f32 v[72:73], v[72:73], v[220:221] op_sel:[0,1]
	v_pk_mul_f32 v[74:75], v[74:75], v[220:221] op_sel:[0,1]
	v_exp_f32_e32 v84, v84
	v_exp_f32_e32 v85, v85
	v_exp_f32_e32 v86, v86
	v_exp_f32_e32 v87, v87
	v_exp_f32_e32 v76, v76
	v_exp_f32_e32 v77, v77
	v_exp_f32_e32 v78, v78
	v_exp_f32_e32 v79, v79
	v_exp_f32_e32 v80, v80
	v_exp_f32_e32 v81, v81
	v_exp_f32_e32 v82, v82
	v_exp_f32_e32 v83, v83
	v_exp_f32_e32 v72, v72
	v_exp_f32_e32 v73, v73
	v_exp_f32_e32 v74, v74
	v_exp_f32_e32 v75, v75
	v_pk_add_f32 v[84:85], v[84:85], s[70:71]
	v_pk_add_f32 v[86:87], v[86:87], s[70:71]
	v_pk_add_f32 v[76:77], v[76:77], s[70:71]
	v_pk_add_f32 v[78:79], v[78:79], s[70:71]
	v_pk_add_f32 v[80:81], v[80:81], s[70:71]
	v_pk_add_f32 v[82:83], v[82:83], s[70:71]
	v_pk_add_f32 v[72:73], v[72:73], s[70:71]
	v_pk_add_f32 v[74:75], v[74:75], s[70:71]
	v_rcp_f32_e32 v84, v84
	v_rcp_f32_e32 v85, v85
	v_rcp_f32_e32 v86, v86
	v_rcp_f32_e32 v87, v87
	v_rcp_f32_e32 v76, v76
	v_rcp_f32_e32 v77, v77
	v_rcp_f32_e32 v78, v78
	v_rcp_f32_e32 v79, v79
	v_rcp_f32_e32 v80, v80
	v_rcp_f32_e32 v81, v81
	v_rcp_f32_e32 v82, v82
	v_rcp_f32_e32 v83, v83
	v_rcp_f32_e32 v72, v72
	v_rcp_f32_e32 v73, v73
	v_rcp_f32_e32 v74, v74
	v_rcp_f32_e32 v75, v75
	s_waitcnt vmcnt(16)
	v_lshlrev_b32_e32 v36, 16, v248
	v_and_b32_e32 v37, 0xffff0000, v248
	v_lshlrev_b32_e32 v38, 16, v152
	v_and_b32_e32 v39, 0xffff0000, v152
	v_lshlrev_b32_e32 v48, 16, v249
	v_and_b32_e32 v49, 0xffff0000, v249
	v_lshlrev_b32_e32 v50, 16, v153
	v_and_b32_e32 v51, 0xffff0000, v153
	v_pk_mul_f32 v[36:37], v[36:37], v[136:137]
	v_pk_mul_f32 v[38:39], v[38:39], v[144:145]
	v_pk_mul_f32 v[48:49], v[48:49], v[138:139]
	v_pk_mul_f32 v[50:51], v[50:51], v[146:147]
	v_pk_mul_f32 v[84:85], v[84:85], v[36:37]
	v_pk_mul_f32 v[80:81], v[80:81], v[38:39]
	v_pk_mul_f32 v[86:87], v[86:87], v[48:49]
	v_pk_mul_f32 v[82:83], v[82:83], v[50:51]
	v_pk_mul_f32 v[84:85], v[84:85], v[222:223] op_sel_hi:[1,0]
	v_pk_mul_f32 v[86:87], v[86:87], v[222:223] op_sel_hi:[1,0]
	v_pk_fma_f32 v[84:85], v[80:81], v[222:223], v[84:85] op_sel:[0,1,0]
	v_pk_fma_f32 v[86:87], v[82:83], v[222:223], v[86:87] op_sel:[0,1,0]
	v_lshlrev_b32_e32 v36, 16, v250
	v_and_b32_e32 v37, 0xffff0000, v250
	v_lshlrev_b32_e32 v38, 16, v154
	v_and_b32_e32 v39, 0xffff0000, v154
	v_lshlrev_b32_e32 v48, 16, v251
	v_and_b32_e32 v49, 0xffff0000, v251
	v_lshlrev_b32_e32 v50, 16, v155
	v_and_b32_e32 v51, 0xffff0000, v155
	v_pk_mul_f32 v[36:37], v[36:37], v[140:141]
	v_pk_mul_f32 v[38:39], v[38:39], v[148:149]
	v_pk_mul_f32 v[48:49], v[48:49], v[142:143]
	v_pk_mul_f32 v[50:51], v[50:51], v[150:151]
	v_pk_mul_f32 v[76:77], v[76:77], v[36:37]
	v_pk_mul_f32 v[72:73], v[72:73], v[38:39]
	v_pk_mul_f32 v[78:79], v[78:79], v[48:49]
	v_pk_mul_f32 v[74:75], v[74:75], v[50:51]
	v_pk_mul_f32 v[76:77], v[76:77], v[222:223] op_sel_hi:[1,0]
	v_pk_mul_f32 v[78:79], v[78:79], v[222:223] op_sel_hi:[1,0]
	v_pk_fma_f32 v[76:77], v[72:73], v[222:223], v[76:77] op_sel:[0,1,0]
	v_pk_fma_f32 v[78:79], v[74:75], v[222:223], v[78:79] op_sel:[0,1,0]
	s_nop 0
	v_cvt_pk_bf16_f32 v84, v84, v85
	v_cvt_pk_bf16_f32 v85, v86, v87
	v_cvt_pk_bf16_f32 v86, v76, v77
	v_cvt_pk_bf16_f32 v87, v78, v79
	v_lshl_add_u64 v[188:189], v[188:189], 0, s[72:73]
	global_store_dwordx4 v[188:189], v[84:87], off
	global_load_dword v221, v[180:181], off offset:704
	global_load_dword v222, v[184:185], off offset:704
	global_load_dword v223, v[186:187], off offset:704
	s_waitcnt vmcnt(22)
;     __device__ __forceinline__ void operator()(const pg8::f32x4 (&acc)[2][2][4][2], const pg8::Unit& u, int wr, int wc, int fr, int fq) const {
;         const int row0 = u.pm * 256 + wr * 64 + fr, col0 = u.pn * 128 + wc * 32 + 8 * fq;
;         const pg8::f32x4 wa0 = *(const pg8::f32x4*)(wa + col0), wa1 = *(const pg8::f32x4*)(wa + col0 + 4), ws0 = *(const pg8::f32x4*)(wsn + col0), ws1 = *(const pg8::f32x4*)(wsn + col0 + 4);
;         float rsv[8], rav[8], rbv[8];
; #pragma unroll
;         for (int q = 0; q < 8; ++q) { const int row = row0 + (q >> 2) * 128 + (q & 3) * 16; rsv[q] = rstd[row]; rav[q] = rowsa[row]; rbv[q] = rowsb[row]; }
; #pragma unroll
;         for (int p = 0; p < 4; ++p) {
;             u32x4 awv[2], swv[2];
; #pragma unroll
;             for (int m2 = 0; m2 < 2; ++m2) { const int q = p * 2 + m2; const size_t off = (size_t)(row0 + (q >> 2) * 128 + (q & 3) * 16) * DM + col0; awv[m2] = *(const u32x4*)(ATT + off); swv[m2] = *(const u32x4*)(SSM + off); }
;             asm volatile("" : "+v"(awv[0]), "+v"(awv[1]), "+v"(swv[0]), "+v"(swv[1]));
; #pragma unroll
;             for (int m2 = 0; m2 < 2; ++m2) { const int q = p * 2 + m2, ai = q >> 2, m = q & 3; const int row = row0 + ai * 128 + m * 16; const size_t off = (size_t)row * DM + col0;
;                 const u32x4 aw = awv[m2], sw = swv[m2];
;                 const float rs = rsv[q], ra = __builtin_amdgcn_rsqf(rav[q] * (1.0f / DM) + EPS), rb = __builtin_amdgcn_rsqf(rbv[q] * (1.0f / DM) + EPS);
;                 const float av[8] = {bf_lo(aw.x), bf_hi(aw.x), bf_lo(aw.y), bf_hi(aw.y), bf_lo(aw.z), bf_hi(aw.z), bf_lo(aw.w), bf_hi(aw.w)};
;                 const float sv[8] = {bf_lo(sw.x), bf_hi(sw.x), bf_lo(sw.y), bf_hi(sw.y), bf_lo(sw.z), bf_hi(sw.z), bf_lo(sw.w), bf_hi(sw.w)};
;                 float o[8];
; #pragma unroll
;                 for (int n = 0; n < 2; ++n)
; #pragma unroll
;                     for (int e = 0; e < 4; ++e) { const float wl = n ? wa1[e] : wa0[e], vl = n ? ws1[e] : ws0[e];
;                         o[n * 4 + e] = fast_sigmoid(acc[ai][0][m][n][e] * rs) * av[n * 4 + e] * (ra * wl) + fast_sigmoid(acc[ai][1][m][n][e] * rs) * sv[n * 4 + e] * (rb * vl); }
;                 u32x4 w; w.x = cvt_pk(o[0], o[1]); w.y = cvt_pk(o[2], o[3]); w.z = cvt_pk(o[4], o[5]); w.w = cvt_pk(o[6], o[7]);
;                 *(u32x4*)(MG + off) = w; }
	v_fmaak_f32 v213, v194, v213, 0x358637bd
	v_fmaak_f32 v214, v194, v214, 0x358637bd
	v_mul_f32_e32 v212, 0xbfb8aa3b, v212
	v_rsq_f32_e32 v213, v213
	v_rsq_f32_e32 v214, v214
	v_pk_mul_f32 v[68:69], v[68:69], v[212:213] op_sel_hi:[1,0]
	v_pk_mul_f32 v[70:71], v[70:71], v[212:213] op_sel_hi:[1,0]
	v_pk_mul_f32 v[60:61], v[60:61], v[212:213] op_sel_hi:[1,0]
	v_pk_mul_f32 v[62:63], v[62:63], v[212:213] op_sel_hi:[1,0]
	v_pk_mul_f32 v[64:65], v[64:65], v[212:213] op_sel_hi:[1,0]
	v_pk_mul_f32 v[66:67], v[66:67], v[212:213] op_sel_hi:[1,0]
	v_pk_mul_f32 v[56:57], v[56:57], v[212:213] op_sel_hi:[1,0]
	v_pk_mul_f32 v[58:59], v[58:59], v[212:213] op_sel_hi:[1,0]
	v_exp_f32_e32 v68, v68
	v_exp_f32_e32 v69, v69
	v_exp_f32_e32 v70, v70
	v_exp_f32_e32 v71, v71
	v_exp_f32_e32 v60, v60
	v_exp_f32_e32 v61, v61
	v_exp_f32_e32 v62, v62
	v_exp_f32_e32 v63, v63
	v_exp_f32_e32 v64, v64
	v_exp_f32_e32 v65, v65
	v_exp_f32_e32 v66, v66
	v_exp_f32_e32 v67, v67
	v_exp_f32_e32 v56, v56
	v_exp_f32_e32 v57, v57
	v_exp_f32_e32 v58, v58
	v_exp_f32_e32 v59, v59
	v_pk_add_f32 v[68:69], v[68:69], s[70:71]
	v_pk_add_f32 v[70:71], v[70:71], s[70:71]
	v_pk_add_f32 v[60:61], v[60:61], s[70:71]
	v_pk_add_f32 v[62:63], v[62:63], s[70:71]
	v_pk_add_f32 v[64:65], v[64:65], s[70:71]
	v_pk_add_f32 v[66:67], v[66:67], s[70:71]
	v_pk_add_f32 v[56:57], v[56:57], s[70:71]
	v_pk_add_f32 v[58:59], v[58:59], s[70:71]
	v_rcp_f32_e32 v68, v68
	v_rcp_f32_e32 v69, v69
	v_rcp_f32_e32 v70, v70
	v_rcp_f32_e32 v71, v71
	v_rcp_f32_e32 v60, v60
	v_rcp_f32_e32 v61, v61
	v_rcp_f32_e32 v62, v62
	v_rcp_f32_e32 v63, v63
	v_rcp_f32_e32 v64, v64
	v_rcp_f32_e32 v65, v65
	v_rcp_f32_e32 v66, v66
	v_rcp_f32_e32 v67, v67
	v_rcp_f32_e32 v56, v56
	v_rcp_f32_e32 v57, v57
	v_rcp_f32_e32 v58, v58
	v_rcp_f32_e32 v59, v59
	s_waitcnt vmcnt(18)
	v_lshlrev_b32_e32 v36, 16, v156
	v_and_b32_e32 v37, 0xffff0000, v156
	v_lshlrev_b32_e32 v38, 16, v124
	v_and_b32_e32 v39, 0xffff0000, v124
	v_lshlrev_b32_e32 v48, 16, v157
	v_and_b32_e32 v49, 0xffff0000, v157
	v_lshlrev_b32_e32 v50, 16, v125
	v_and_b32_e32 v51, 0xffff0000, v125
	v_pk_mul_f32 v[36:37], v[36:37], v[136:137]
	v_pk_mul_f32 v[38:39], v[38:39], v[144:145]
	v_pk_mul_f32 v[48:49], v[48:49], v[138:139]
	v_pk_mul_f32 v[50:51], v[50:51], v[146:147]
	v_pk_mul_f32 v[68:69], v[68:69], v[36:37]
	v_pk_mul_f32 v[64:65], v[64:65], v[38:39]
	v_pk_mul_f32 v[70:71], v[70:71], v[48:49]
	v_pk_mul_f32 v[66:67], v[66:67], v[50:51]
	v_pk_mul_f32 v[68:69], v[68:69], v[212:213] op_sel:[0,1]
	v_pk_mul_f32 v[70:71], v[70:71], v[212:213] op_sel:[0,1]
	v_pk_fma_f32 v[68:69], v[64:65], v[214:215], v[68:69] op_sel_hi:[1,0,1]
	v_pk_fma_f32 v[70:71], v[66:67], v[214:215], v[70:71] op_sel_hi:[1,0,1]
	v_lshlrev_b32_e32 v36, 16, v158
	v_and_b32_e32 v37, 0xffff0000, v158
	v_lshlrev_b32_e32 v38, 16, v126
	v_and_b32_e32 v39, 0xffff0000, v126
	v_lshlrev_b32_e32 v48, 16, v159
	v_and_b32_e32 v49, 0xffff0000, v159
	v_lshlrev_b32_e32 v50, 16, v127
	v_and_b32_e32 v51, 0xffff0000, v127
	v_pk_mul_f32 v[36:37], v[36:37], v[140:141]
	v_pk_mul_f32 v[38:39], v[38:39], v[148:149]
	v_pk_mul_f32 v[48:49], v[48:49], v[142:143]
	v_pk_mul_f32 v[50:51], v[50:51], v[150:151]
	v_pk_mul_f32 v[60:61], v[60:61], v[36:37]
	v_pk_mul_f32 v[56:57], v[56:57], v[38:39]
	v_pk_mul_f32 v[62:63], v[62:63], v[48:49]
	v_pk_mul_f32 v[58:59], v[58:59], v[50:51]
	v_pk_mul_f32 v[60:61], v[60:61], v[212:213] op_sel:[0,1]
	v_pk_mul_f32 v[62:63], v[62:63], v[212:213] op_sel:[0,1]
	v_pk_fma_f32 v[60:61], v[56:57], v[214:215], v[60:61] op_sel_hi:[1,0,1]
	v_pk_fma_f32 v[62:63], v[58:59], v[214:215], v[62:63] op_sel_hi:[1,0,1]
	s_nop 0
	v_cvt_pk_bf16_f32 v68, v68, v69
	v_cvt_pk_bf16_f32 v69, v70, v71
	v_cvt_pk_bf16_f32 v70, v60, v61
	v_cvt_pk_bf16_f32 v71, v62, v63
	v_lshl_add_u64 v[188:189], v[188:189], 0, s[74:75]
	global_store_dwordx4 v[188:189], v[68:71], off
	s_waitcnt vmcnt(13)
	v_fmaak_f32 v216, v194, v216, 0x358637bd
	v_fmaak_f32 v217, v194, v217, 0x358637bd
	v_mul_f32_e32 v215, 0xbfb8aa3b, v215
	v_rsq_f32_e32 v216, v216
	v_rsq_f32_e32 v217, v217
	v_pk_mul_f32 v[52:53], v[52:53], v[214:215] op_sel:[0,1]
	v_pk_mul_f32 v[54:55], v[54:55], v[214:215] op_sel:[0,1]
	v_pk_mul_f32 v[40:41], v[40:41], v[214:215] op_sel:[0,1]
	v_pk_mul_f32 v[42:43], v[42:43], v[214:215] op_sel:[0,1]
	v_pk_mul_f32 v[44:45], v[44:45], v[214:215] op_sel:[0,1]
	v_pk_mul_f32 v[46:47], v[46:47], v[214:215] op_sel:[0,1]
	v_pk_mul_f32 v[32:33], v[32:33], v[214:215] op_sel:[0,1]
	v_pk_mul_f32 v[34:35], v[34:35], v[214:215] op_sel:[0,1]
	v_exp_f32_e32 v52, v52
	v_exp_f32_e32 v53, v53
	v_exp_f32_e32 v54, v54
	v_exp_f32_e32 v55, v55
	v_exp_f32_e32 v40, v40
	v_exp_f32_e32 v41, v41
	v_exp_f32_e32 v42, v42
	v_exp_f32_e32 v43, v43
	v_exp_f32_e32 v44, v44
	v_exp_f32_e32 v45, v45
	v_exp_f32_e32 v46, v46
	v_exp_f32_e32 v47, v47
	v_exp_f32_e32 v32, v32
	v_exp_f32_e32 v33, v33
	v_exp_f32_e32 v34, v34
	v_exp_f32_e32 v35, v35
	v_pk_add_f32 v[52:53], v[52:53], s[70:71]
	v_pk_add_f32 v[54:55], v[54:55], s[70:71]
	v_pk_add_f32 v[40:41], v[40:41], s[70:71]
	v_pk_add_f32 v[42:43], v[42:43], s[70:71]
	v_pk_add_f32 v[44:45], v[44:45], s[70:71]
	v_pk_add_f32 v[46:47], v[46:47], s[70:71]
	v_pk_add_f32 v[32:33], v[32:33], s[70:71]
	v_pk_add_f32 v[34:35], v[34:35], s[70:71]
	v_rcp_f32_e32 v52, v52
	v_rcp_f32_e32 v53, v53
	v_rcp_f32_e32 v54, v54
	v_rcp_f32_e32 v55, v55
	v_rcp_f32_e32 v40, v40
	v_rcp_f32_e32 v41, v41
	v_rcp_f32_e32 v42, v42
	v_rcp_f32_e32 v43, v43
	v_rcp_f32_e32 v44, v44
	v_rcp_f32_e32 v45, v45
	v_rcp_f32_e32 v46, v46
	v_rcp_f32_e32 v47, v47
	v_rcp_f32_e32 v32, v32
	v_rcp_f32_e32 v33, v33
	v_rcp_f32_e32 v34, v34
	v_rcp_f32_e32 v35, v35
	s_waitcnt vmcnt(17)
;     __device__ __forceinline__ void operator()(const pg8::f32x4 (&acc)[2][2][4][2], const pg8::Unit& u, int wr, int wc, int fr, int fq) const {
;         const int row0 = u.pm * 256 + wr * 64 + fr, col0 = u.pn * 128 + wc * 32 + 8 * fq;
;         const pg8::f32x4 wa0 = *(const pg8::f32x4*)(wa + col0), wa1 = *(const pg8::f32x4*)(wa + col0 + 4), ws0 = *(const pg8::f32x4*)(wsn + col0), ws1 = *(const pg8::f32x4*)(wsn + col0 + 4);
;         float rsv[8], rav[8], rbv[8];
; #pragma unroll
;         for (int q = 0; q < 8; ++q) { const int row = row0 + (q >> 2) * 128 + (q & 3) * 16; rsv[q] = rstd[row]; rav[q] = rowsa[row]; rbv[q] = rowsb[row]; }
; #pragma unroll
;         for (int p = 0; p < 4; ++p) {
;             u32x4 awv[2], swv[2];
; #pragma unroll
;             for (int m2 = 0; m2 < 2; ++m2) { const int q = p * 2 + m2; const size_t off = (size_t)(row0 + (q >> 2) * 128 + (q & 3) * 16) * DM + col0; awv[m2] = *(const u32x4*)(ATT + off); swv[m2] = *(const u32x4*)(SSM + off); }
;             asm volatile("" : "+v"(awv[0]), "+v"(awv[1]), "+v"(swv[0]), "+v"(swv[1]));
; #pragma unroll
;             for (int m2 = 0; m2 < 2; ++m2) { const int q = p * 2 + m2, ai = q >> 2, m = q & 3; const int row = row0 + ai * 128 + m * 16; const size_t off = (size_t)row * DM + col0;
;                 const u32x4 aw = awv[m2], sw = swv[m2];
;                 const float rs = rsv[q], ra = __builtin_amdgcn_rsqf(rav[q] * (1.0f / DM) + EPS), rb = __builtin_amdgcn_rsqf(rbv[q] * (1.0f / DM) + EPS);
;                 const float av[8] = {bf_lo(aw.x), bf_hi(aw.x), bf_lo(aw.y), bf_hi(aw.y), bf_lo(aw.z), bf_hi(aw.z), bf_lo(aw.w), bf_hi(aw.w)};
;                 const float sv[8] = {bf_lo(sw.x), bf_hi(sw.x), bf_lo(sw.y), bf_hi(sw.y), bf_lo(sw.z), bf_hi(sw.z), bf_lo(sw.w), bf_hi(sw.w)};
;                 float o[8];
; #pragma unroll
;                 for (int n = 0; n < 2; ++n)
; #pragma unroll
;                     for (int e = 0; e < 4; ++e) { const float wl = n ? wa1[e] : wa0[e], vl = n ? ws1[e] : ws0[e];
;                         o[n * 4 + e] = fast_sigmoid(acc[ai][0][m][n][e] * rs) * av[n * 4 + e] * (ra * wl) + fast_sigmoid(acc[ai][1][m][n][e] * rs) * sv[n * 4 + e] * (rb * vl); }
;                 u32x4 w; w.x = cvt_pk(o[0], o[1]); w.y = cvt_pk(o[2], o[3]); w.z = cvt_pk(o[4], o[5]); w.w = cvt_pk(o[6], o[7]);
;                 *(u32x4*)(MG + off) = w; }
	v_lshlrev_b32_e32 v36, 16, v128
	v_and_b32_e32 v37, 0xffff0000, v128
	v_lshlrev_b32_e32 v38, 16, v120
	v_and_b32_e32 v39, 0xffff0000, v120
	v_lshlrev_b32_e32 v48, 16, v129
	v_and_b32_e32 v49, 0xffff0000, v129
	v_lshlrev_b32_e32 v50, 16, v121
	v_and_b32_e32 v51, 0xffff0000, v121
	v_pk_mul_f32 v[36:37], v[36:37], v[136:137]
	v_pk_mul_f32 v[38:39], v[38:39], v[144:145]
	v_pk_mul_f32 v[48:49], v[48:49], v[138:139]
	v_pk_mul_f32 v[50:51], v[50:51], v[146:147]
	v_pk_mul_f32 v[52:53], v[52:53], v[36:37]
	v_pk_mul_f32 v[44:45], v[44:45], v[38:39]
	v_pk_mul_f32 v[54:55], v[54:55], v[48:49]
	v_pk_mul_f32 v[46:47], v[46:47], v[50:51]
	v_pk_mul_f32 v[52:53], v[52:53], v[216:217] op_sel_hi:[1,0]
	v_pk_mul_f32 v[54:55], v[54:55], v[216:217] op_sel_hi:[1,0]
	v_pk_fma_f32 v[52:53], v[44:45], v[216:217], v[52:53] op_sel:[0,1,0]
	v_pk_fma_f32 v[54:55], v[46:47], v[216:217], v[54:55] op_sel:[0,1,0]
	v_lshlrev_b32_e32 v36, 16, v130
	v_and_b32_e32 v37, 0xffff0000, v130
	v_lshlrev_b32_e32 v38, 16, v122
	v_and_b32_e32 v39, 0xffff0000, v122
	v_lshlrev_b32_e32 v48, 16, v131
	v_and_b32_e32 v49, 0xffff0000, v131
	v_lshlrev_b32_e32 v50, 16, v123
	v_and_b32_e32 v51, 0xffff0000, v123
	v_pk_mul_f32 v[36:37], v[36:37], v[140:141]
	v_pk_mul_f32 v[38:39], v[38:39], v[148:149]
	v_pk_mul_f32 v[48:49], v[48:49], v[142:143]
	v_pk_mul_f32 v[50:51], v[50:51], v[150:151]
	v_pk_mul_f32 v[40:41], v[40:41], v[36:37]
	v_pk_mul_f32 v[32:33], v[32:33], v[38:39]
	v_pk_mul_f32 v[42:43], v[42:43], v[48:49]
	v_pk_mul_f32 v[34:35], v[34:35], v[50:51]
	v_pk_mul_f32 v[40:41], v[40:41], v[216:217] op_sel_hi:[1,0]
	v_pk_mul_f32 v[42:43], v[42:43], v[216:217] op_sel_hi:[1,0]
	v_pk_fma_f32 v[40:41], v[32:33], v[216:217], v[40:41] op_sel:[0,1,0]
	v_pk_fma_f32 v[42:43], v[34:35], v[216:217], v[42:43] op_sel:[0,1,0]
	s_nop 0
	v_cvt_pk_bf16_f32 v52, v52, v53
	v_cvt_pk_bf16_f32 v53, v54, v55
	v_cvt_pk_bf16_f32 v54, v40, v41
	v_cvt_pk_bf16_f32 v55, v42, v43
	v_lshl_add_u64 v[188:189], v[188:189], 0, s[72:73]
	global_store_dwordx4 v[188:189], v[52:55], off
	s_waitcnt vmcnt(6)
	v_fmaak_f32 v219, v194, v219, 0x358637bd
	v_fmaak_f32 v220, v194, v220, 0x358637bd
	v_mul_f32_e32 v218, 0xbfb8aa3b, v218
	v_rsq_f32_e32 v219, v219
	v_rsq_f32_e32 v220, v220
	v_pk_mul_f32 v[28:29], v[28:29], v[218:219] op_sel_hi:[1,0]
	v_pk_mul_f32 v[30:31], v[30:31], v[218:219] op_sel_hi:[1,0]
	v_pk_mul_f32 v[20:21], v[20:21], v[218:219] op_sel_hi:[1,0]
	v_pk_mul_f32 v[22:23], v[22:23], v[218:219] op_sel_hi:[1,0]
	v_pk_mul_f32 v[24:25], v[24:25], v[218:219] op_sel_hi:[1,0]
	v_pk_mul_f32 v[26:27], v[26:27], v[218:219] op_sel_hi:[1,0]
	v_pk_mul_f32 v[16:17], v[16:17], v[218:219] op_sel_hi:[1,0]
	v_pk_mul_f32 v[18:19], v[18:19], v[218:219] op_sel_hi:[1,0]
	v_exp_f32_e32 v28, v28
	v_exp_f32_e32 v29, v29
	v_exp_f32_e32 v30, v30
	v_exp_f32_e32 v31, v31
	v_exp_f32_e32 v20, v20
	v_exp_f32_e32 v21, v21
	v_exp_f32_e32 v22, v22
	v_exp_f32_e32 v23, v23
	v_exp_f32_e32 v24, v24
	v_exp_f32_e32 v25, v25
	v_exp_f32_e32 v26, v26
	v_exp_f32_e32 v27, v27
	v_exp_f32_e32 v16, v16
	v_exp_f32_e32 v17, v17
	v_exp_f32_e32 v18, v18
	v_exp_f32_e32 v19, v19
	v_pk_add_f32 v[28:29], v[28:29], s[70:71]
	v_pk_add_f32 v[30:31], v[30:31], s[70:71]
	v_pk_add_f32 v[20:21], v[20:21], s[70:71]
	v_pk_add_f32 v[22:23], v[22:23], s[70:71]
	v_pk_add_f32 v[24:25], v[24:25], s[70:71]
	v_pk_add_f32 v[26:27], v[26:27], s[70:71]
	v_pk_add_f32 v[16:17], v[16:17], s[70:71]
	v_pk_add_f32 v[18:19], v[18:19], s[70:71]
	v_rcp_f32_e32 v28, v28
	v_rcp_f32_e32 v29, v29
	v_rcp_f32_e32 v30, v30
	v_rcp_f32_e32 v31, v31
	v_rcp_f32_e32 v20, v20
	v_rcp_f32_e32 v21, v21
	v_rcp_f32_e32 v22, v22
	v_rcp_f32_e32 v23, v23
	v_rcp_f32_e32 v24, v24
	v_rcp_f32_e32 v25, v25
	v_rcp_f32_e32 v26, v26
	v_rcp_f32_e32 v27, v27
	v_rcp_f32_e32 v16, v16
	v_rcp_f32_e32 v17, v17
	v_rcp_f32_e32 v18, v18
	v_rcp_f32_e32 v19, v19
	s_waitcnt vmcnt(12)
	v_lshlrev_b32_e32 v36, 16, v196
	v_and_b32_e32 v37, 0xffff0000, v196
	v_lshlrev_b32_e32 v38, 16, v252
	v_and_b32_e32 v39, 0xffff0000, v252
	v_lshlrev_b32_e32 v48, 16, v197
	v_and_b32_e32 v49, 0xffff0000, v197
	v_lshlrev_b32_e32 v50, 16, v253
	v_and_b32_e32 v51, 0xffff0000, v253
	v_pk_mul_f32 v[36:37], v[36:37], v[136:137]
	v_pk_mul_f32 v[38:39], v[38:39], v[144:145]
	v_pk_mul_f32 v[48:49], v[48:49], v[138:139]
	v_pk_mul_f32 v[50:51], v[50:51], v[146:147]
	v_pk_mul_f32 v[28:29], v[28:29], v[36:37]
	v_pk_mul_f32 v[24:25], v[24:25], v[38:39]
	v_pk_mul_f32 v[30:31], v[30:31], v[48:49]
	v_pk_mul_f32 v[26:27], v[26:27], v[50:51]
	v_pk_mul_f32 v[28:29], v[28:29], v[218:219] op_sel:[0,1]
	v_pk_mul_f32 v[30:31], v[30:31], v[218:219] op_sel:[0,1]
	v_pk_fma_f32 v[28:29], v[24:25], v[220:221], v[28:29] op_sel_hi:[1,0,1]
	v_pk_fma_f32 v[30:31], v[26:27], v[220:221], v[30:31] op_sel_hi:[1,0,1]
	v_lshlrev_b32_e32 v36, 16, v198
	v_and_b32_e32 v37, 0xffff0000, v198
	v_lshlrev_b32_e32 v38, 16, v254
	v_and_b32_e32 v39, 0xffff0000, v254
	v_lshlrev_b32_e32 v48, 16, v199
	v_and_b32_e32 v49, 0xffff0000, v199
	v_lshlrev_b32_e32 v50, 16, v255
	v_and_b32_e32 v51, 0xffff0000, v255
	v_pk_mul_f32 v[36:37], v[36:37], v[140:141]
	v_pk_mul_f32 v[38:39], v[38:39], v[148:149]
	v_pk_mul_f32 v[48:49], v[48:49], v[142:143]
	v_pk_mul_f32 v[50:51], v[50:51], v[150:151]
	v_pk_mul_f32 v[20:21], v[20:21], v[36:37]
	v_pk_mul_f32 v[16:17], v[16:17], v[38:39]
	v_pk_mul_f32 v[22:23], v[22:23], v[48:49]
	v_pk_mul_f32 v[18:19], v[18:19], v[50:51]
	v_pk_mul_f32 v[20:21], v[20:21], v[218:219] op_sel:[0,1]
	v_pk_mul_f32 v[22:23], v[22:23], v[218:219] op_sel:[0,1]
	v_pk_fma_f32 v[20:21], v[16:17], v[220:221], v[20:21] op_sel_hi:[1,0,1]
	v_pk_fma_f32 v[22:23], v[18:19], v[220:221], v[22:23] op_sel_hi:[1,0,1]
	s_nop 0
	v_cvt_pk_bf16_f32 v28, v28, v29
	v_cvt_pk_bf16_f32 v29, v30, v31
	v_cvt_pk_bf16_f32 v30, v20, v21
	v_cvt_pk_bf16_f32 v31, v22, v23
	v_lshl_add_u64 v[188:189], v[188:189], 0, s[72:73]
	global_store_dwordx4 v[188:189], v[28:31], off
	s_waitcnt vmcnt(3)
; __device__ __forceinline__ unsigned cvt_pk(float lo, float hi) { unsigned r; asm volatile("v_cvt_pk_bf16_f32 %0, %1, %2" : "=v"(r) : "v"(lo), "v"(hi)); return r; }
; __device__ __forceinline__ float bf_lo(unsigned w) { return __uint_as_float(w << 16); }
; __device__ __forceinline__ float bf_hi(unsigned w) { return __uint_as_float(w & 0xffff0000u); }
; __device__ __forceinline__ float fast_sigmoid(float v) { return __builtin_amdgcn_rcpf(1.0f + __builtin_amdgcn_exp2f(-1.4426950408889634f * v)); }
;     __device__ __forceinline__ void operator()(const pg8::f32x4 (&acc)[2][2][4][2], const pg8::Unit& u, int wr, int wc, int fr, int fq) const {
;     ...
;             for (int m2 = 0; m2 < 2; ++m2) { const int q = p * 2 + m2, ai = q >> 2, m = q & 3; const int row = row0 + ai * 128 + m * 16; const size_t off = (size_t)row * DM + col0;
;                 const u32x4 aw = awv[m2], sw = swv[m2];
;                 const float rs = rsv[q], ra = __builtin_amdgcn_rsqf(rav[q] * (1.0f / DM) + EPS), rb = __builtin_amdgcn_rsqf(rbv[q] * (1.0f / DM) + EPS);
;                 const float av[8] = {bf_lo(aw.x), bf_hi(aw.x), bf_lo(aw.y), bf_hi(aw.y), bf_lo(aw.z), bf_hi(aw.z), bf_lo(aw.w), bf_hi(aw.w)};
;                 const float sv[8] = {bf_lo(sw.x), bf_hi(sw.x), bf_lo(sw.y), bf_hi(sw.y), bf_lo(sw.z), bf_hi(sw.z), bf_lo(sw.w), bf_hi(sw.w)};
;                 float o[8];
; #pragma unroll
;                 for (int n = 0; n < 2; ++n)
; #pragma unroll
;                     for (int e = 0; e < 4; ++e) { const float wl = n ? wa1[e] : wa0[e], vl = n ? ws1[e] : ws0[e];
;                         o[n * 4 + e] = fast_sigmoid(acc[ai][0][m][n][e] * rs) * av[n * 4 + e] * (ra * wl) + fast_sigmoid(acc[ai][1][m][n][e] * rs) * sv[n * 4 + e] * (rb * vl); }
;                 u32x4 w; w.x = cvt_pk(o[0], o[1]); w.y = cvt_pk(o[2], o[3]); w.z = cvt_pk(o[4], o[5]); w.w = cvt_pk(o[6], o[7]);
;                 *(u32x4*)(MG + off) = w; }
	v_fmaak_f32 v222, v194, v222, 0x358637bd
	v_fmaak_f32 v223, v194, v223, 0x358637bd
	v_mul_f32_e32 v221, 0xbfb8aa3b, v221
	v_rsq_f32_e32 v222, v222
	v_rsq_f32_e32 v223, v223
	v_pk_mul_f32 v[12:13], v[12:13], v[220:221] op_sel:[0,1]
	v_pk_mul_f32 v[14:15], v[14:15], v[220:221] op_sel:[0,1]
	v_pk_mul_f32 v[4:5], v[4:5], v[220:221] op_sel:[0,1]
	v_pk_mul_f32 v[6:7], v[6:7], v[220:221] op_sel:[0,1]
	v_pk_mul_f32 v[8:9], v[8:9], v[220:221] op_sel:[0,1]
	v_pk_mul_f32 v[10:11], v[10:11], v[220:221] op_sel:[0,1]
	v_pk_mul_f32 v[0:1], v[0:1], v[220:221] op_sel:[0,1]
	v_pk_mul_f32 v[2:3], v[2:3], v[220:221] op_sel:[0,1]
	v_exp_f32_e32 v12, v12
	v_exp_f32_e32 v13, v13
	v_exp_f32_e32 v14, v14
	v_exp_f32_e32 v15, v15
	v_exp_f32_e32 v4, v4
	v_exp_f32_e32 v5, v5
	v_exp_f32_e32 v6, v6
	v_exp_f32_e32 v7, v7
	v_exp_f32_e32 v8, v8
	v_exp_f32_e32 v9, v9
	v_exp_f32_e32 v10, v10
	v_exp_f32_e32 v11, v11
	v_exp_f32_e32 v0, v0
	v_exp_f32_e32 v1, v1
	v_exp_f32_e32 v2, v2
	v_exp_f32_e32 v3, v3
	v_pk_add_f32 v[12:13], v[12:13], s[70:71]
	v_pk_add_f32 v[14:15], v[14:15], s[70:71]
	v_pk_add_f32 v[4:5], v[4:5], s[70:71]
	v_pk_add_f32 v[6:7], v[6:7], s[70:71]
	v_pk_add_f32 v[8:9], v[8:9], s[70:71]
	v_pk_add_f32 v[10:11], v[10:11], s[70:71]
	v_pk_add_f32 v[0:1], v[0:1], s[70:71]
	v_pk_add_f32 v[2:3], v[2:3], s[70:71]
	v_rcp_f32_e32 v12, v12
	v_rcp_f32_e32 v13, v13
	v_rcp_f32_e32 v14, v14
	v_rcp_f32_e32 v15, v15
	v_rcp_f32_e32 v4, v4
	v_rcp_f32_e32 v5, v5
	v_rcp_f32_e32 v6, v6
	v_rcp_f32_e32 v7, v7
	v_rcp_f32_e32 v8, v8
	v_rcp_f32_e32 v9, v9
	v_rcp_f32_e32 v10, v10
	v_rcp_f32_e32 v11, v11
	v_rcp_f32_e32 v0, v0
	v_rcp_f32_e32 v1, v1
	v_rcp_f32_e32 v2, v2
	v_rcp_f32_e32 v3, v3
	s_waitcnt vmcnt(11)
	v_lshlrev_b32_e32 v36, 16, v108
	v_and_b32_e32 v37, 0xffff0000, v108
	v_lshlrev_b32_e32 v38, 16, v112
	v_and_b32_e32 v39, 0xffff0000, v112
	v_lshlrev_b32_e32 v48, 16, v109
	v_and_b32_e32 v49, 0xffff0000, v109
	v_lshlrev_b32_e32 v50, 16, v113
	v_and_b32_e32 v51, 0xffff0000, v113
	v_pk_mul_f32 v[36:37], v[36:37], v[136:137]
	v_pk_mul_f32 v[38:39], v[38:39], v[144:145]
	v_pk_mul_f32 v[48:49], v[48:49], v[138:139]
	v_pk_mul_f32 v[50:51], v[50:51], v[146:147]
	v_pk_mul_f32 v[12:13], v[12:13], v[36:37]
	v_pk_mul_f32 v[8:9], v[8:9], v[38:39]
	v_pk_mul_f32 v[14:15], v[14:15], v[48:49]
	v_pk_mul_f32 v[10:11], v[10:11], v[50:51]
	v_pk_mul_f32 v[12:13], v[12:13], v[222:223] op_sel_hi:[1,0]
	v_pk_mul_f32 v[14:15], v[14:15], v[222:223] op_sel_hi:[1,0]
	v_pk_fma_f32 v[12:13], v[8:9], v[222:223], v[12:13] op_sel:[0,1,0]
	v_pk_fma_f32 v[14:15], v[10:11], v[222:223], v[14:15] op_sel:[0,1,0]
	v_lshlrev_b32_e32 v36, 16, v110
	v_and_b32_e32 v37, 0xffff0000, v110
	v_lshlrev_b32_e32 v38, 16, v114
	v_and_b32_e32 v39, 0xffff0000, v114
	v_lshlrev_b32_e32 v48, 16, v111
	v_and_b32_e32 v49, 0xffff0000, v111
	v_lshlrev_b32_e32 v50, 16, v115
	v_and_b32_e32 v51, 0xffff0000, v115
	v_pk_mul_f32 v[36:37], v[36:37], v[140:141]
	v_pk_mul_f32 v[38:39], v[38:39], v[148:149]
	v_pk_mul_f32 v[48:49], v[48:49], v[142:143]
	v_pk_mul_f32 v[50:51], v[50:51], v[150:151]
	v_pk_mul_f32 v[4:5], v[4:5], v[36:37]
	v_pk_mul_f32 v[0:1], v[0:1], v[38:39]
	v_pk_mul_f32 v[6:7], v[6:7], v[48:49]
	v_pk_mul_f32 v[2:3], v[2:3], v[50:51]
	v_pk_mul_f32 v[4:5], v[4:5], v[222:223] op_sel_hi:[1,0]
	v_pk_mul_f32 v[6:7], v[6:7], v[222:223] op_sel_hi:[1,0]
	v_pk_fma_f32 v[4:5], v[0:1], v[222:223], v[4:5] op_sel:[0,1,0]
	v_pk_fma_f32 v[6:7], v[2:3], v[222:223], v[6:7] op_sel:[0,1,0]
	s_nop 0
	v_cvt_pk_bf16_f32 v12, v12, v13
	v_cvt_pk_bf16_f32 v13, v14, v15
	v_cvt_pk_bf16_f32 v14, v4, v5
	v_cvt_pk_bf16_f32 v15, v6, v7
	v_lshl_add_u64 v[188:189], v[188:189], 0, s[72:73]
	global_store_dwordx4 v[188:189], v[12:15], off
	s_mov_b64 s[28:29], -1
	s_andn2_b64 vcc, exec, s[0:1]
	s_cbranch_vccnz .LBB0_496
	s_andn2_b64 vcc, exec, s[4:5]
	s_cbranch_vccnz .LBB0_495
	s_barrier
	s_branch .LBB0_495
